# static s_setprio 1 for waves 4-7 during the three GEMM phases (no per-phase flips)
# baseline (speedup 1.0000x reference)
.LBB0_229:
	v_readfirstlane_b32 s100, v180
	s_nop 3
	s_cmp_lt_u32 s100, 0x100
	s_cbranch_scc1 .Lprio_a
	s_setprio 1

.LBB0_290:
	s_setprio 0
	v_readlane_b32 s8, v254, 16
	s_cmp_ge_i32 s2, s3
	v_readlane_b32 s9, v254, 17
	s_cselect_b64 s[6:7], -1, 0
	s_xor_b64 s[8:9], s[8:9], -1
	s_and_b64 s[6:7], s[8:9], s[6:7]
	s_and_b64 vcc, exec, s[6:7]
	s_mov_b32 s92, s4
	s_cbranch_vccz .LBB0_364
	s_sub_i32 s62, s2, s3
	s_cmpk_lt_u32 s62, 0x300
	s_cselect_b64 s[6:7], -1, 0
	s_cmpk_gt_u32 s62, 0x2ff
	s_cbranch_scc1 .LBB0_293
	v_mov_b32_e32 v0, 0x100
	v_sub_co_u32_e32 v0, vcc, s62, v0
	s_and_b64 s[8:9], vcc, exec
	v_readfirstlane_b32 s8, v0
	v_readlane_b32 s64, v254, 0
	s_cselect_b32 s8, s62, s8
	v_readlane_b32 s66, v254, 2
	v_readlane_b32 s67, v254, 3
	v_readlane_b32 s70, v254, 6
	v_readlane_b32 s71, v254, 7
	s_sext_i32_i16 s9, s8
	s_cselect_b32 s3, s67, s71
	s_cselect_b32 s10, s66, s70
	s_bfe_u32 s9, s9, 0x3001c
	s_add_i32 s9, s8, s9
	s_sext_i32_i16 s11, s9
	s_and_b32 s9, s9, 0xfff8
	s_sub_i32 s8, s8, s9
	s_lshl_b32 s9, s11, 3
	s_sext_i32_i16 s8, s8
	s_and_b32 s11, s9, 0xffffffc0
	s_lshl_b32 s8, s8, 8
	s_waitcnt vmcnt(0)
	v_or_b32_e32 v24, s11, v176
	s_ashr_i32 s9, s8, 31
	v_ashrrev_i32_e32 v25, 31, v24
	s_lshl_b64 s[8:9], s[8:9], 2
	v_lshlrev_b64 v[0:1], 13, v[24:25]
	v_or_b32_e32 v2, s11, v155
	v_or_b32_e32 v8, 16, v24
	v_or_b32_e32 v10, s11, v156
	v_or_b32_e32 v16, 32, v24
	v_or_b32_e32 v18, s11, v157
	v_or_b32_e32 v24, 48, v24
	v_add_u32_e32 v26, s11, v158
	s_add_u32 s8, s10, s8
	v_ashrrev_i32_e32 v3, 31, v2
	v_ashrrev_i32_e32 v9, 31, v8
	v_ashrrev_i32_e32 v11, 31, v10
	v_ashrrev_i32_e32 v17, 31, v16
	v_ashrrev_i32_e32 v19, 31, v18
	v_ashrrev_i32_e32 v25, 31, v24
	v_ashrrev_i32_e32 v27, 31, v26
	s_addc_u32 s9, s3, s9
	v_lshlrev_b64 v[2:3], 13, v[2:3]
	v_lshlrev_b64 v[8:9], 13, v[8:9]
	v_lshlrev_b64 v[10:11], 13, v[10:11]
	v_lshlrev_b64 v[16:17], 13, v[16:17]
	v_lshlrev_b64 v[18:19], 13, v[18:19]
	v_lshlrev_b64 v[24:25], 13, v[24:25]
	v_lshlrev_b64 v[26:27], 13, v[26:27]
	v_lshl_add_u64 v[0:1], s[8:9], 0, v[0:1]
	v_mov_b32_e32 v129, 0
	v_lshl_add_u64 v[2:3], s[8:9], 0, v[2:3]
	v_lshl_add_u64 v[8:9], s[8:9], 0, v[8:9]
	v_lshl_add_u64 v[10:11], s[8:9], 0, v[10:11]
	v_lshl_add_u64 v[16:17], s[8:9], 0, v[16:17]
	v_lshl_add_u64 v[18:19], s[8:9], 0, v[18:19]
	v_lshl_add_u64 v[24:25], s[8:9], 0, v[24:25]
	v_lshl_add_u64 v[26:27], s[8:9], 0, v[26:27]
	v_lshl_add_u64 v[0:1], v[0:1], 0, v[128:129]
	v_lshl_add_u64 v[4:5], v[2:3], 0, v[128:129]
	v_lshl_add_u64 v[8:9], v[8:9], 0, v[128:129]
	v_lshl_add_u64 v[12:13], v[10:11], 0, v[128:129]
	v_lshl_add_u64 v[16:17], v[16:17], 0, v[128:129]
	v_lshl_add_u64 v[20:21], v[18:19], 0, v[128:129]
	v_lshl_add_u64 v[24:25], v[24:25], 0, v[128:129]
	v_lshl_add_u64 v[28:29], v[26:27], 0, v[128:129]
	global_load_dwordx4 v[0:3], v[0:1], off nt
	s_nop 0
	global_load_dwordx4 v[4:7], v[4:5], off nt
	s_nop 0
	global_load_dwordx4 v[8:11], v[8:9], off nt
	s_nop 0
	global_load_dwordx4 v[12:15], v[12:13], off nt
	s_nop 0
	global_load_dwordx4 v[16:19], v[16:17], off nt
	s_nop 0
	global_load_dwordx4 v[20:23], v[20:21], off nt
	s_nop 0
	global_load_dwordx4 v[24:27], v[24:25], off nt
	s_nop 0
	global_load_dwordx4 v[28:31], v[28:29], off nt
	v_readlane_b32 s3, v254, 10
	v_readlane_b32 s65, v254, 1
	v_readlane_b32 s68, v254, 4
	v_readlane_b32 s69, v254, 5

.LBB0_542:
	s_and_b32 s27, s22, 3
	s_mov_b64 s[22:23], 0x80
	s_add_i32 m0, s61, 0x18000
	v_lshl_add_u64 v[6:7], v[6:7], 0, s[22:23]
	s_lshl_b32 s34, s3, 6
	s_lshl_b32 s3, s3, 13
	s_lshl_b32 s36, s27, 12
	s_waitcnt vmcnt(4)
	s_barrier
	global_load_lds_dwordx4 v[6:7], off
	v_lshl_add_u64 v[4:5], v[4:5], 0, s[22:23]
	s_add_i32 m0, s61, 0x1a000
	s_add_i32 s71, s61, 0x8000
	s_add_i32 s74, s61, 0xa000
	global_load_lds_dwordx4 v[4:5], off
	v_lshl_add_u64 v[2:3], v[2:3], 0, s[22:23]
	s_mov_b32 m0, s71
	s_add_u32 s38, s28, 0x80080
	global_load_lds_dwordx4 v[2:3], off
	v_lshl_add_u64 v[0:1], v[0:1], 0, s[22:23]
	s_mov_b32 m0, s74
	s_addc_u32 s39, s29, 0
	global_load_lds_dwordx4 v[0:1], off
	s_add_i32 m0, s61, 0x1c000
	v_lshl_add_u64 v[0:1], s[38:39], 0, v[184:185]
	global_load_lds_dwordx4 v[0:1], off
	v_lshl_add_u64 v[0:1], s[38:39], 0, v[188:189]
	s_add_i32 m0, s61, 0x1e000
	v_lshlrev_b32_e32 v2, 2, v210
	global_load_lds_dwordx4 v[0:1], off
	v_lshl_or_b32 v1, v210, 6, v141
	v_and_b32_e32 v2, 32, v2
	v_bitop3_b32 v2, v1, s3, v2 bitop3:0xde
	s_lshl_b32 s3, s27, 4
	v_or_b32_e32 v225, s34, v210
	s_or_b32 s34, s3, s34
	s_lshl_b64 s[38:39], s[34:35], 10
	s_add_u32 s3, s58, s24
	s_addc_u32 s25, s59, s25
	v_lshlrev_b32_e32 v0, 3, v140
	s_add_u32 s24, s3, s38
	v_or_b32_e32 v1, v141, v218
	v_lshl_or_b32 v227, s27, 5, v0
	s_addc_u32 s25, s25, s39
	v_lshlrev_b32_e32 v0, 4, v210
	s_ashr_i32 s76, s2, 31
	v_bitop3_b32 v226, s36, v1, v219 bitop3:0xf6
	v_lshl_or_b32 v0, v140, 8, v0
	v_mov_b32_e32 v1, v185
	s_cmp_eq_u64 s[20:21], 0
	v_lshl_add_u64 v[190:191], s[24:25], 0, v[0:1]
	s_cselect_b64 s[24:25], -1, 0
	s_lshr_b32 s3, s76, 29
	s_add_i32 s3, s2, s3
	s_ashr_i32 s27, s3, 3
	s_add_i32 s26, s27, s26
	s_ashr_i32 s27, s26, 31
	s_lshr_b32 s27, s27, 29
	s_add_i32 s27, s26, s27
	s_and_b32 s3, s3, 0xfffff8
	v_lshlrev_b32_e32 v0, 9, v180
	s_ashr_i32 s34, s27, 3
	s_and_b32 s27, s27, -8
	s_sub_i32 s3, s2, s3
	v_and_b32_e32 v0, 0xffff0000, v0
	v_lshlrev_b32_e32 v1, 12, v216
	s_sub_i32 s26, s26, s27
	s_lshl_b32 s77, s3, 8
	v_or3_b32 v0, v214, v0, v1
	s_cmp_lt_i32 s26, 0
	v_add_u32_e32 v192, v0, v215
	v_lshlrev_b32_e32 v0, 5, v217
	s_waitcnt vmcnt(6)
	s_cselect_b32 s3, 37, 36
	v_and_b32_e32 v0, 0xffff0000, v0
	s_mul_i32 s78, s26, s3
	v_or3_b32 v0, v214, v0, v1
	s_add_i32 s79, 0, 0x10000
	s_add_i32 s80, 0, 0x14000
	s_mov_b32 s75, s30
	s_add_i32 s78, s78, s34
	v_mov_b32_e32 v193, v185
	v_add_u32_e32 v194, v0, v215
	v_mov_b32_e32 v195, v185
	v_add_u32_e32 v228, s79, v226
	v_add_u32_e32 v229, 0, v2
	v_add_u32_e32 v230, s80, v226
	s_mov_b64 s[26:27], 0x3c00
	s_mov_b32 s36, 0xbfb8aa3b
	s_movk_i32 s81, 0x1000
	v_mov_b64_e32 v[196:197], 0x120
	s_barrier
	v_readfirstlane_b32 s100, v180
	s_nop 3
	s_cmp_lt_u32 s100, 0x100
	s_cbranch_scc1 .Lprio_b
	s_setprio 1
.Lprio_b:
	s_branch .LBB0_545
.LBB0_543:
	s_or_b64 exec, exec, s[10:11]

.LBB0_568:
	s_setprio 0
	s_waitcnt vmcnt(0)
	s_cmpk_gt_u32 s68, 0xff
	s_cbranch_scc1 .LBB0_570
	s_barrier

.LBB0_637:
	s_mov_b64 s[16:17], 0x80
	s_and_b32 s5, s11, 3
	s_add_i32 m0, s44, 0x18000
	v_lshl_add_u64 v[6:7], v[6:7], 0, s[16:17]
	s_lshl_b32 s40, s10, 6
	s_lshl_b32 s18, s10, 13
	s_lshl_b32 s19, s5, 12
	s_lshl_b32 s65, s5, 5
	s_lshl_b32 s66, s6, 9
	s_waitcnt vmcnt(4)
	s_barrier
	global_load_lds_dwordx4 v[6:7], off
	v_lshl_add_u64 v[4:5], v[4:5], 0, s[16:17]
	s_add_i32 m0, s44, 0x1a000
	s_add_i32 s67, s44, 0x8000
	s_add_i32 s68, s44, 0xa000
	global_load_lds_dwordx4 v[4:5], off
	v_lshl_add_u64 v[2:3], v[2:3], 0, s[16:17]
	s_mov_b32 m0, s67
	s_add_u32 s10, s8, 0x100080
	global_load_lds_dwordx4 v[2:3], off
	v_lshl_add_u64 v[0:1], v[0:1], 0, s[16:17]
	s_mov_b32 m0, s68
	s_addc_u32 s11, s9, 0
	global_load_lds_dwordx4 v[0:1], off
	s_add_i32 m0, s44, 0x1c000
	v_lshl_add_u64 v[0:1], s[10:11], 0, v[134:135]
	global_load_lds_dwordx4 v[0:1], off
	v_lshl_add_u64 v[0:1], s[10:11], 0, v[136:137]
	s_add_i32 m0, s44, 0x1e000
	v_lshrrev_b32_e32 v148, 7, v180
	global_load_lds_dwordx4 v[0:1], off
	v_lshlrev_b32_e32 v1, 2, v210
	v_lshl_or_b32 v0, v210, 6, v224
	v_and_b32_e32 v1, 32, v1
	v_bitop3_b32 v0, v0, s18, v1 bitop3:0xde
	v_or_b32_e32 v1, v218, v224
	v_bitop3_b32 v139, s19, v1, v219 bitop3:0xf6
	v_lshlrev_b32_e32 v1, 17, v148
	v_lshlrev_b32_e32 v2, 13, v216
	v_or3_b32 v1, v214, v1, v2
	v_add_u32_e32 v56, v1, v215
	v_lshlrev_b32_e32 v1, 6, v217
	v_and_b32_e32 v1, 0xfffe0000, v1
	s_mov_b64 s[10:11], 0x100080
	v_or3_b32 v1, v214, v1, v2
	v_lshl_add_u64 v[142:143], v[56:57], 0, s[10:11]
	v_add_u32_e32 v56, v1, v215
	v_or_b32_e32 v132, s40, v210
	s_waitcnt vmcnt(6)
	v_mov_b32_e32 v133, v57
	v_lshl_add_u64 v[144:145], v[56:57], 0, s[10:11]
	v_mov_b32_e32 v56, v57
	v_mov_b32_e32 v58, v57
	v_mov_b32_e32 v59, v57
	s_add_i32 s71, 0, 0x10000
	s_add_i32 s72, 0, 0x14000
	s_lshl_b32 s69, s6, 2
	v_lshlrev_b64 v[140:141], 9, v[132:133]
	v_add_u32_e32 v133, 0, v0
	s_add_i32 s75, s71, s41
	s_add_i32 s77, s72, s41
	v_mov_b64_e32 v[0:1], v[56:57]
	v_mov_b64_e32 v[4:5], v[56:57]
	v_mov_b64_e32 v[16:17], v[56:57]
	v_mov_b64_e32 v[20:21], v[56:57]
	v_mov_b64_e32 v[32:33], v[56:57]
	v_mov_b64_e32 v[36:37], v[56:57]
	v_mov_b64_e32 v[48:49], v[56:57]
	v_mov_b64_e32 v[52:53], v[56:57]
	v_mov_b64_e32 v[8:9], v[56:57]
	v_mov_b64_e32 v[12:13], v[56:57]
	v_mov_b64_e32 v[24:25], v[56:57]
	v_mov_b64_e32 v[28:29], v[56:57]
	v_mov_b64_e32 v[40:41], v[56:57]
	v_mov_b64_e32 v[44:45], v[56:57]
	v_mov_b64_e32 v[62:63], v[58:59]
	v_mov_b64_e32 v[66:67], v[58:59]
	v_mov_b64_e32 v[70:71], v[58:59]
	v_mov_b64_e32 v[74:75], v[58:59]
	v_mov_b64_e32 v[86:87], v[58:59]
	v_mov_b64_e32 v[90:91], v[58:59]
	v_mov_b64_e32 v[102:103], v[58:59]
	v_mov_b64_e32 v[106:107], v[58:59]
	v_mov_b64_e32 v[118:119], v[58:59]
	v_mov_b64_e32 v[122:123], v[58:59]
	v_mov_b64_e32 v[78:79], v[58:59]
	v_mov_b64_e32 v[82:83], v[58:59]
	v_mov_b64_e32 v[94:95], v[58:59]
	v_mov_b64_e32 v[98:99], v[58:59]
	v_mov_b64_e32 v[110:111], v[58:59]
	v_mov_b64_e32 v[114:115], v[58:59]
	v_mov_b64_e32 v[126:127], v[58:59]
	v_mov_b64_e32 v[130:131], v[58:59]
	s_add_i32 s69, s69, s3
	s_or_b32 s70, s33, 0xffffff00
	v_and_b32_e32 v138, 12, v177
	s_lshl_b32 s18, s65, 1
	s_add_i32 s73, s44, 0xc000
	s_add_i32 s74, s44, 0xe000
	s_add_i32 s76, s75, 0x2000
	s_add_i32 s78, s77, 0x2000
	s_add_i32 s79, 0, 0x18000
	v_mov_b64_e32 v[2:3], v[58:59]
	v_mov_b64_e32 v[6:7], v[58:59]
	v_mov_b64_e32 v[18:19], v[58:59]
	v_mov_b64_e32 v[22:23], v[58:59]
	v_mov_b64_e32 v[34:35], v[58:59]
	v_mov_b64_e32 v[38:39], v[58:59]
	v_mov_b64_e32 v[50:51], v[58:59]
	v_mov_b64_e32 v[54:55], v[58:59]
	v_mov_b64_e32 v[10:11], v[58:59]
	v_mov_b64_e32 v[14:15], v[58:59]
	v_mov_b64_e32 v[26:27], v[58:59]
	v_mov_b64_e32 v[30:31], v[58:59]
	v_mov_b64_e32 v[42:43], v[58:59]
	v_mov_b64_e32 v[46:47], v[58:59]
	v_mov_b64_e32 v[60:61], v[56:57]
	v_mov_b64_e32 v[64:65], v[56:57]
	v_mov_b64_e32 v[68:69], v[56:57]
	v_mov_b64_e32 v[72:73], v[56:57]
	v_mov_b64_e32 v[84:85], v[56:57]
	v_mov_b64_e32 v[88:89], v[56:57]
	v_mov_b64_e32 v[100:101], v[56:57]
	v_mov_b64_e32 v[104:105], v[56:57]
	v_mov_b64_e32 v[116:117], v[56:57]
	v_mov_b64_e32 v[120:121], v[56:57]
	v_mov_b64_e32 v[76:77], v[56:57]
	v_mov_b64_e32 v[80:81], v[56:57]
	v_mov_b64_e32 v[92:93], v[56:57]
	v_mov_b64_e32 v[96:97], v[56:57]
	v_mov_b64_e32 v[108:109], v[56:57]
	v_mov_b64_e32 v[112:113], v[56:57]
	v_mov_b64_e32 v[124:125], v[56:57]
	v_mov_b64_e32 v[128:129], v[56:57]
	s_mov_b32 s19, s4
	s_mov_b32 s6, s66
	s_mov_b32 s80, 0
	s_barrier
	v_readfirstlane_b32 s100, v180
	s_nop 3
	s_cmp_lt_u32 s100, 0x100
	s_cbranch_scc1 .Lprio_c
	s_setprio 1
.Lprio_c:
	s_branch .LBB0_639
.LBB0_638:
	s_and_b64 s[22:23], s[26:27], exec
	s_cselect_b32 s49, 8, 64
	s_lshl_b32 s3, s19, 3
	s_add_i32 s22, s70, s3
	s_lshr_b32 s6, s6, 9
	s_ashr_i32 s23, s22, 31
	s_lshl_b64 s[26:27], s[6:7], 22
	s_add_u32 s3, s58, s26
	s_addc_u32 s6, s59, s27
	s_lshl_b64 s[22:23], s[22:23], 17
	s_add_u32 s22, s3, s22
	s_addc_u32 s23, s6, s23
	v_lshl_add_u64 v[58:59], s[22:23], 0, v[140:141]
	s_mov_b32 s19, s7
	v_lshl_add_u64 v[58:59], v[58:59], 0, s[18:19]
	v_lshlrev_b32_e32 v56, 1, v138
	v_lshl_add_u64 v[58:59], v[58:59], 0, v[56:57]
	v_cvt_pk_bf16_f32 v112, v112, v113
	v_cvt_pk_bf16_f32 v113, v114, v115
	v_add_co_u32_e32 v114, vcc, s51, v58
	v_cvt_pk_bf16_f32 v96, v96, v97
	v_cvt_pk_bf16_f32 v97, v98, v99
	v_cvt_pk_bf16_f32 v80, v80, v81
	v_cvt_pk_bf16_f32 v81, v82, v83
	s_nop 1
	v_addc_co_u32_e32 v115, vcc, 0, v59, vcc
	v_add_co_u32_e32 v98, vcc, s62, v58
	v_cvt_pk_bf16_f32 v64, v64, v65
	v_cvt_pk_bf16_f32 v65, v66, v67
	v_cvt_pk_bf16_f32 v44, v44, v45
	v_cvt_pk_bf16_f32 v45, v46, v47
	s_nop 1
	v_addc_co_u32_e32 v99, vcc, 0, v59, vcc
	v_add_co_u32_e32 v82, vcc, s63, v58
	v_cvt_pk_bf16_f32 v28, v28, v29
	v_cvt_pk_bf16_f32 v29, v30, v31
	v_cvt_pk_bf16_f32 v12, v12, v13
	v_cvt_pk_bf16_f32 v13, v14, v15
	s_nop 1
	v_addc_co_u32_e32 v83, vcc, 0, v59, vcc
	v_add_co_u32_e32 v66, vcc, s48, v58
	v_cvt_pk_bf16_f32 v0, v0, v1
	v_cvt_pk_bf16_f32 v128, v128, v129
	v_cvt_pk_bf16_f32 v129, v130, v131
	v_cvt_pk_bf16_f32 v124, v124, v125
	s_nop 1
	v_addc_co_u32_e32 v67, vcc, 0, v59, vcc
	v_add_co_u32_e32 v46, vcc, s50, v58
	v_cvt_pk_bf16_f32 v125, v126, v127
	v_cvt_pk_bf16_f32 v120, v120, v121
	v_cvt_pk_bf16_f32 v121, v122, v123
	v_cvt_pk_bf16_f32 v116, v116, v117
	s_nop 1
	v_addc_co_u32_e32 v47, vcc, 0, v59, vcc
	v_add_co_u32_e32 v30, vcc, s60, v58
	v_cvt_pk_bf16_f32 v117, v118, v119
	v_cvt_pk_bf16_f32 v108, v108, v109
	v_cvt_pk_bf16_f32 v109, v110, v111
	v_cvt_pk_bf16_f32 v104, v104, v105
	s_nop 1
	v_addc_co_u32_e32 v31, vcc, 0, v59, vcc
	v_add_co_u32_e32 v14, vcc, s61, v58
	v_cvt_pk_bf16_f32 v105, v106, v107
	v_cvt_pk_bf16_f32 v100, v100, v101
	v_cvt_pk_bf16_f32 v101, v102, v103
	v_cvt_pk_bf16_f32 v92, v92, v93
	s_nop 1
	v_addc_co_u32_e32 v15, vcc, 0, v59, vcc
	v_cvt_pk_bf16_f32 v93, v94, v95
	v_cvt_pk_bf16_f32 v88, v88, v89
	v_cvt_pk_bf16_f32 v89, v90, v91
	v_cvt_pk_bf16_f32 v84, v84, v85
	v_cvt_pk_bf16_f32 v85, v86, v87
	v_cvt_pk_bf16_f32 v76, v76, v77
	v_cvt_pk_bf16_f32 v77, v78, v79
	v_cvt_pk_bf16_f32 v72, v72, v73
	v_cvt_pk_bf16_f32 v73, v74, v75
	v_cvt_pk_bf16_f32 v68, v68, v69
	v_cvt_pk_bf16_f32 v69, v70, v71
	v_cvt_pk_bf16_f32 v60, v60, v61
	v_cvt_pk_bf16_f32 v61, v62, v63
	v_cvt_pk_bf16_f32 v52, v52, v53
	v_cvt_pk_bf16_f32 v53, v54, v55
	v_cvt_pk_bf16_f32 v48, v48, v49
	v_cvt_pk_bf16_f32 v49, v50, v51
	v_cvt_pk_bf16_f32 v40, v40, v41
	v_cvt_pk_bf16_f32 v41, v42, v43
	v_cvt_pk_bf16_f32 v36, v36, v37
	v_cvt_pk_bf16_f32 v37, v38, v39
	v_cvt_pk_bf16_f32 v32, v32, v33
	v_cvt_pk_bf16_f32 v33, v34, v35
	v_cvt_pk_bf16_f32 v24, v24, v25
	v_cvt_pk_bf16_f32 v25, v26, v27
	v_cvt_pk_bf16_f32 v20, v20, v21
	v_cvt_pk_bf16_f32 v21, v22, v23
	v_cvt_pk_bf16_f32 v16, v16, v17
	v_cvt_pk_bf16_f32 v17, v18, v19
	v_cvt_pk_bf16_f32 v8, v8, v9
	v_cvt_pk_bf16_f32 v9, v10, v11
	v_cvt_pk_bf16_f32 v4, v4, v5
	v_cvt_pk_bf16_f32 v5, v6, v7
	v_cvt_pk_bf16_f32 v1, v2, v3
	global_store_dwordx2 v[14:15], v[0:1], off offset:288
	v_mov_b32_e32 v0, 0
	global_store_dwordx2 v[58:59], v[128:129], off
	global_store_dwordx2 v[58:59], v[124:125], off offset:32
	global_store_dwordx2 v[58:59], v[120:121], off offset:256
	global_store_dwordx2 v[58:59], v[116:117], off offset:288
	global_store_dwordx2 v[114:115], v[112:113], off
	global_store_dwordx2 v[114:115], v[108:109], off offset:32
	global_store_dwordx2 v[114:115], v[104:105], off offset:256
	global_store_dwordx2 v[114:115], v[100:101], off offset:288
	global_store_dwordx2 v[98:99], v[96:97], off
	global_store_dwordx2 v[98:99], v[92:93], off offset:32
	global_store_dwordx2 v[98:99], v[88:89], off offset:256
	global_store_dwordx2 v[98:99], v[84:85], off offset:288
	global_store_dwordx2 v[82:83], v[80:81], off
	global_store_dwordx2 v[82:83], v[76:77], off offset:32
	global_store_dwordx2 v[82:83], v[72:73], off offset:256
	global_store_dwordx2 v[82:83], v[68:69], off offset:288
	global_store_dwordx2 v[66:67], v[64:65], off
	global_store_dwordx2 v[66:67], v[60:61], off offset:32
	global_store_dwordx2 v[66:67], v[52:53], off offset:256
	global_store_dwordx2 v[66:67], v[48:49], off offset:288
	global_store_dwordx2 v[46:47], v[44:45], off
	global_store_dwordx2 v[46:47], v[40:41], off offset:32
	global_store_dwordx2 v[46:47], v[36:37], off offset:256
	global_store_dwordx2 v[46:47], v[32:33], off offset:288
	global_store_dwordx2 v[30:31], v[28:29], off
	global_store_dwordx2 v[30:31], v[24:25], off offset:32
	global_store_dwordx2 v[30:31], v[20:21], off offset:256
	global_store_dwordx2 v[30:31], v[16:17], off offset:288
	global_store_dwordx2 v[14:15], v[12:13], off
	global_store_dwordx2 v[14:15], v[8:9], off offset:32
	global_store_dwordx2 v[14:15], v[4:5], off offset:256
	s_mov_b32 s19, s10
	s_mov_b32 s6, s82
	s_mov_b64 s[22:23], s[24:25]
	s_mov_b32 s80, s81
	v_mov_b32_e32 v1, v0
	v_mov_b32_e32 v2, v0
	v_mov_b32_e32 v3, v0
	v_mov_b32_e32 v4, v0
	v_mov_b32_e32 v5, v0
	v_mov_b32_e32 v6, v0
	v_mov_b32_e32 v7, v0
	v_mov_b32_e32 v16, v0
	v_mov_b32_e32 v17, v0
	v_mov_b32_e32 v18, v0
	v_mov_b32_e32 v19, v0
	v_mov_b32_e32 v20, v0
	v_mov_b32_e32 v21, v0
	v_mov_b32_e32 v22, v0
	v_mov_b32_e32 v23, v0
	v_mov_b32_e32 v32, v0
	v_mov_b32_e32 v33, v0
	v_mov_b32_e32 v34, v0
	v_mov_b32_e32 v35, v0
	v_mov_b32_e32 v36, v0
	v_mov_b32_e32 v37, v0
	v_mov_b32_e32 v38, v0
	v_mov_b32_e32 v39, v0
	v_mov_b32_e32 v48, v0
	v_mov_b32_e32 v49, v0
	v_mov_b32_e32 v50, v0
	v_mov_b32_e32 v51, v0
	v_mov_b32_e32 v52, v0
	v_mov_b32_e32 v53, v0
	v_mov_b32_e32 v54, v0
	v_mov_b32_e32 v55, v0
	v_mov_b32_e32 v8, v0
	v_mov_b32_e32 v9, v0
	v_mov_b32_e32 v10, v0
	v_mov_b32_e32 v11, v0
	v_mov_b32_e32 v12, v0
	v_mov_b32_e32 v13, v0
	v_mov_b32_e32 v14, v0
	v_mov_b32_e32 v15, v0
	v_mov_b32_e32 v24, v0
	v_mov_b32_e32 v25, v0
	v_mov_b32_e32 v26, v0
	v_mov_b32_e32 v27, v0
	v_mov_b32_e32 v28, v0
	v_mov_b32_e32 v29, v0
	v_mov_b32_e32 v30, v0
	v_mov_b32_e32 v31, v0
	v_mov_b32_e32 v40, v0
	v_mov_b32_e32 v41, v0
	v_mov_b32_e32 v42, v0
	v_mov_b32_e32 v43, v0
	v_mov_b32_e32 v44, v0
	v_mov_b32_e32 v45, v0
	v_mov_b32_e32 v46, v0
	v_mov_b32_e32 v47, v0
	v_mov_b32_e32 v60, v0
	v_mov_b32_e32 v61, v0
	v_mov_b32_e32 v62, v0
	v_mov_b32_e32 v63, v0
	v_mov_b32_e32 v64, v0
	v_mov_b32_e32 v65, v0
	v_mov_b32_e32 v66, v0
	v_mov_b32_e32 v67, v0
	v_mov_b32_e32 v68, v0
	v_mov_b32_e32 v69, v0
	v_mov_b32_e32 v70, v0
	v_mov_b32_e32 v71, v0
	v_mov_b32_e32 v72, v0
	v_mov_b32_e32 v73, v0
	v_mov_b32_e32 v74, v0
	v_mov_b32_e32 v75, v0
	v_mov_b32_e32 v84, v0
	v_mov_b32_e32 v85, v0
	v_mov_b32_e32 v86, v0
	v_mov_b32_e32 v87, v0
	v_mov_b32_e32 v88, v0
	v_mov_b32_e32 v89, v0
	v_mov_b32_e32 v90, v0
	v_mov_b32_e32 v91, v0
	v_mov_b32_e32 v100, v0
	v_mov_b32_e32 v101, v0
	v_mov_b32_e32 v102, v0
	v_mov_b32_e32 v103, v0
	v_mov_b32_e32 v104, v0
	v_mov_b32_e32 v105, v0
	v_mov_b32_e32 v106, v0
	v_mov_b32_e32 v107, v0
	v_mov_b32_e32 v116, v0
	v_mov_b32_e32 v117, v0
	v_mov_b32_e32 v118, v0
	v_mov_b32_e32 v119, v0
	v_mov_b32_e32 v120, v0
	v_mov_b32_e32 v121, v0
	v_mov_b32_e32 v122, v0
	v_mov_b32_e32 v123, v0
	v_mov_b32_e32 v76, v0
	v_mov_b32_e32 v77, v0
	v_mov_b32_e32 v78, v0
	v_mov_b32_e32 v79, v0
	v_mov_b32_e32 v80, v0
	v_mov_b32_e32 v81, v0
	v_mov_b32_e32 v82, v0
	v_mov_b32_e32 v83, v0
	v_mov_b32_e32 v92, v0
	v_mov_b32_e32 v93, v0
	v_mov_b32_e32 v94, v0
	v_mov_b32_e32 v95, v0
	v_mov_b32_e32 v96, v0
	v_mov_b32_e32 v97, v0
	v_mov_b32_e32 v98, v0
	v_mov_b32_e32 v99, v0
	v_mov_b32_e32 v108, v0
	v_mov_b32_e32 v109, v0
	v_mov_b32_e32 v110, v0
	v_mov_b32_e32 v111, v0
	v_mov_b32_e32 v112, v0
	v_mov_b32_e32 v113, v0
	v_mov_b32_e32 v114, v0
	v_mov_b32_e32 v115, v0
	v_mov_b32_e32 v124, v0
	v_mov_b32_e32 v125, v0
	v_mov_b32_e32 v126, v0
	v_mov_b32_e32 v127, v0
	v_mov_b32_e32 v128, v0
	v_mov_b32_e32 v129, v0
	v_mov_b32_e32 v130, v0
	v_mov_b32_e32 v131, v0
	s_andn2_b64 vcc, exec, s[20:21]
	s_cbranch_vccz .LBB0_643

.LBB0_643:
	s_setprio 0
	s_waitcnt vmcnt(0)
	s_cmpk_gt_u32 s30, 0xff
	s_cbranch_scc1 .LBB0_645
	s_barrier

	.amdhsa_kernel _Z9hymba_fwd6Params
		.amdhsa_group_segment_fixed_size 0
		.amdhsa_private_segment_fixed_size 0
		.amdhsa_kernarg_size 440
		.amdhsa_user_sgpr_count 2
		.amdhsa_user_sgpr_dispatch_ptr 0
		.amdhsa_user_sgpr_queue_ptr 0
		.amdhsa_user_sgpr_kernarg_segment_ptr 1
		.amdhsa_user_sgpr_dispatch_id 0
		.amdhsa_user_sgpr_kernarg_preload_length 0
		.amdhsa_user_sgpr_kernarg_preload_offset 0
		.amdhsa_user_sgpr_private_segment_size 0
		.amdhsa_uses_dynamic_stack 0
		.amdhsa_enable_private_segment 0
		.amdhsa_system_sgpr_workgroup_id_x 1
		.amdhsa_system_sgpr_workgroup_id_y 0
		.amdhsa_system_sgpr_workgroup_id_z 0
		.amdhsa_system_sgpr_workgroup_info 0
		.amdhsa_system_vgpr_workitem_id 2
		.amdhsa_next_free_vgpr 255
		.amdhsa_next_free_sgpr 102
		.amdhsa_accum_offset 256
		.amdhsa_reserve_vcc 1
		.amdhsa_float_round_mode_32 0
		.amdhsa_float_round_mode_16_64 0
		.amdhsa_float_denorm_mode_32 3
		.amdhsa_float_denorm_mode_16_64 3
		.amdhsa_dx10_clamp 1
		.amdhsa_ieee_mode 1
		.amdhsa_fp16_overflow 0
		.amdhsa_tg_split 0
		.amdhsa_exception_fp_ieee_invalid_op 0
		.amdhsa_exception_fp_denorm_src 0
		.amdhsa_exception_fp_ieee_div_zero 0
		.amdhsa_exception_fp_ieee_overflow 0
		.amdhsa_exception_fp_ieee_underflow 0
		.amdhsa_exception_fp_ieee_inexact 0
		.amdhsa_exception_int_div_zero 0
	.end_amdhsa_kernel

amdhsa.kernels:
  - .agpr_count:     0
    .args:
      - .offset:         0
        .size:           184
        .value_kind:     by_value
      - .offset:         184
        .size:           4
        .value_kind:     hidden_block_count_x
      - .offset:         188
        .size:           4
        .value_kind:     hidden_block_count_y
      - .offset:         192
        .size:           4
        .value_kind:     hidden_block_count_z
      - .offset:         196
        .size:           2
        .value_kind:     hidden_group_size_x
      - .offset:         198
        .size:           2
        .value_kind:     hidden_group_size_y
      - .offset:         200
        .size:           2
        .value_kind:     hidden_group_size_z
      - .offset:         202
        .size:           2
        .value_kind:     hidden_remainder_x
      - .offset:         204
        .size:           2
        .value_kind:     hidden_remainder_y
      - .offset:         206
        .size:           2
        .value_kind:     hidden_remainder_z
      - .offset:         224
        .size:           8
        .value_kind:     hidden_global_offset_x
      - .offset:         232
        .size:           8
        .value_kind:     hidden_global_offset_y
      - .offset:         240
        .size:           8
        .value_kind:     hidden_global_offset_z
      - .offset:         248
        .size:           2
        .value_kind:     hidden_grid_dims
      - .offset:         272
        .size:           8
        .value_kind:     hidden_multigrid_sync_arg
      - .offset:         304
        .size:           4
        .value_kind:     hidden_dynamic_lds_size
    .group_segment_fixed_size: 0
    .kernarg_segment_align: 8
    .kernarg_segment_size: 440
    .language:       OpenCL C
    .language_version:
      - 2
      - 0
    .max_flat_workgroup_size: 512
    .name:           _Z9hymba_fwd6Params
    .private_segment_fixed_size: 0
    .sgpr_count:     108
    .sgpr_spill_count: 33
    .symbol:         _Z9hymba_fwd6Params.kd
    .uniform_work_group_size: 1
    .uses_dynamic_stack: false
    .vgpr_count:     255
    .vgpr_spill_count: 0
    .wavefront_size: 64
